# attention key loop: second QK block's K reads hoisted above the first PV block (no exposed wait); V ds_write mid-iteration
# baseline (speedup 1.0000x reference)
; #define SB_ __builtin_amdgcn_sched_barrier(0)
; DI void attn_item64(const Params& p, int it, char* smem) {
;     ...
;   for (int kt = 0; kt < NKT; ++kt) {
;     const char* cur = smem + (kt & 1) * STAGE;
;     const bool more = kt + 1 < NKT;
;     if (more) {
;       const bf16_t* kn = Kb + (size_t)(kt + 1) * 64 * QKD; const bf16_t* vn = Vb + (kt + 1) * 64;
;       char* nx = smem + ((kt + 1) & 1) * STAGE;
;       GLDS(kn + kgo0, nx + klo0); if (k1v) GLDS(kn + kgo1, nx + klo1);
;       rv0 = *(const uint4*)(vn + vgo0);
;     }
;     SB_;
; #pragma unroll
;     for (int t2 = 0; t2 < 2; ++t2) {
;       const char* kpe = cur + (t2 * 32 + r) * KROW + swo;
;       const char* kpo = kpe - 2 * sb32;
;       f32x16 sa, sb;
;       { const bf16x8 kf = *(const bf16x8*)(kpe); sa = MFMA(kf, qfa[0], sinit); sb = MFMA(kf, qfb[0], sinit); }
; #pragma unroll
;       for (int c = 1; c < 6; ++c) { const bf16x8 kf = *(const bf16x8*)(((c & 1) ? kpo : kpe) + c * 32); sa = MFMA(kf, qfa[c], sa); sb = MFMA(kf, qfb[c], sb); }
;       SB_;
;       float lsa = 0.f, lsb = 0.f;
; #pragma unroll
;       for (int i = 0; i < 16; ++i) { const float e = __builtin_amdgcn_exp2f(sa[i]); sa[i] = e; lsa += e; const float f = __builtin_amdgcn_exp2f(sb[i]); sb[i] = f; lsb += f; }
;       la += lsa; lb += lsb;
;       SB_;
; #pragma unroll
;       for (int s2 = 0; s2 < 2; ++s2) {
;         uint4 pu, pv;
;         pu.x = pk_bf16(sa[8 * s2 + 0], sa[8 * s2 + 1]); pu.y = pk_bf16(sa[8 * s2 + 2], sa[8 * s2 + 3]); pu.z = pk_bf16(sa[8 * s2 + 4], sa[8 * s2 + 5]); pu.w = pk_bf16(sa[8 * s2 + 6], sa[8 * s2 + 7]);
;         pv.x = pk_bf16(sb[8 * s2 + 0], sb[8 * s2 + 1]); pv.y = pk_bf16(sb[8 * s2 + 2], sb[8 * s2 + 3]); pv.z = pk_bf16(sb[8 * s2 + 4], sb[8 * s2 + 5]); pv.w = pk_bf16(sb[8 * s2 + 6], sb[8 * s2 + 7]);
;         const bf16x8 pa_ = __builtin_bit_cast(bf16x8, pu), pb_ = __builtin_bit_cast(bf16x8, pv);
; #pragma unroll
;         for (int vt = 0; vt < 2; ++vt) {
;           const char* vp = cur + KBYTES + (vt * 32 + r) * VROW + (t2 * 32 + 16 * s2 + 4 * hh) * 2;
;           const uint2 lo = *(const uint2*)(vp), hi = *(const uint2*)(vp + 16);
;           uint4 vu; vu.x = lo.x; vu.y = lo.y; vu.z = hi.x; vu.w = hi.y;
;           const bf16x8 vf = __builtin_bit_cast(bf16x8, vu);
;           oa[vt] = MFMA(vf, pa_, oa[vt]);
;           ob[vt] = MFMA(vf, pb_, ob[vt]);
;         }
;       }
.LBB0_548:
	s_or_b64 exec, exec, s[4:5]
	global_load_dwordx4 v[160:163], v[170:171], off
	s_cmp_eq_u32 s7, 1
	s_cselect_b32 s4, 0, 0x5200
	v_or_b32_e32 v80, s4, v211
	v_add_u32_e32 v80, v80, v210
	v_or_b32_e32 v81, s4, v164
	v_add_u32_e32 v168, v80, v212
	v_add3_u32 v213, v80, v207, v206
	v_add_u32_e32 v80, s6, v209
	v_add_u32_e32 v188, v168, v206
	v_add_u32_e32 v195, v81, v208
	v_add_u32_e32 v238, 0x3000, v80
	ds_read_b128 v[176:179], v168
	ds_read_b128 v[242:245], v188 offset:32
	ds_read_b128 v[180:183], v168 offset:64
	ds_read_b128 v[246:249], v188 offset:96
	ds_read_b128 v[184:187], v168 offset:128
	s_waitcnt lgkmcnt(4)
	v_mfma_f32_32x32x16_bf16 v[80:95], v[176:179], v[152:155], v[64:79]
	v_mfma_f32_32x32x16_bf16 v[96:111], v[176:179], v[156:159], v[64:79]
	ds_read_b128 v[176:179], v188 offset:160
	s_waitcnt lgkmcnt(4)
	v_mfma_f32_32x32x16_bf16 v[80:95], v[242:245], v[136:139], v[80:95]
	v_mfma_f32_32x32x16_bf16 v[96:111], v[242:245], v[140:143], v[96:111]
	s_waitcnt lgkmcnt(3)
	v_mfma_f32_32x32x16_bf16 v[80:95], v[180:183], v[144:147], v[80:95]
	v_mfma_f32_32x32x16_bf16 v[96:111], v[180:183], v[148:151], v[96:111]
	s_waitcnt lgkmcnt(2)
	v_mfma_f32_32x32x16_bf16 v[80:95], v[246:249], v[112:115], v[80:95]
	v_mfma_f32_32x32x16_bf16 v[96:111], v[246:249], v[124:127], v[96:111]
	s_waitcnt lgkmcnt(1)
	v_mfma_f32_32x32x16_bf16 v[80:95], v[184:187], v[128:131], v[80:95]
	v_mfma_f32_32x32x16_bf16 v[96:111], v[184:187], v[132:135], v[96:111]
	s_waitcnt lgkmcnt(0)
	v_mfma_f32_32x32x16_bf16 v[80:95], v[176:179], v[116:119], v[80:95]
	v_mfma_f32_32x32x16_bf16 v[96:111], v[176:179], v[120:123], v[96:111]
	s_nop 10
	v_exp_f32_e32 v214, v80
	v_exp_f32_e32 v215, v81
	v_exp_f32_e32 v216, v82
	v_exp_f32_e32 v217, v83
	v_add_f32_e32 v80, 0, v214
	v_exp_f32_e32 v218, v84
	v_add_f32_e32 v80, v215, v80
	v_exp_f32_e32 v219, v85
	v_add_f32_e32 v80, v216, v80
	v_exp_f32_e32 v222, v86
	v_add_f32_e32 v80, v217, v80
	v_add_f32_e32 v80, v218, v80
	v_add_f32_e32 v80, v219, v80
	v_exp_f32_e32 v96, v96
	v_exp_f32_e32 v97, v97
	v_exp_f32_e32 v98, v98
	v_exp_f32_e32 v99, v99
	v_exp_f32_e32 v100, v100
	v_exp_f32_e32 v101, v101
	v_exp_f32_e32 v102, v102
	v_exp_f32_e32 v188, v87
	v_exp_f32_e32 v189, v103
	v_exp_f32_e32 v186, v88
	v_exp_f32_e32 v187, v104
	v_exp_f32_e32 v190, v89
	v_exp_f32_e32 v191, v105
	v_exp_f32_e32 v192, v90
	v_exp_f32_e32 v193, v106
	v_exp_f32_e32 v180, v91
	v_exp_f32_e32 v181, v107
	v_exp_f32_e32 v182, v92
	v_exp_f32_e32 v183, v108
	v_exp_f32_e32 v184, v93
	v_exp_f32_e32 v185, v109
	v_exp_f32_e32 v176, v94
	v_exp_f32_e32 v177, v110
	v_exp_f32_e32 v178, v95
	v_exp_f32_e32 v179, v111
	v_add_f32_e32 v194, v222, v80
	v_add_u32_e32 v239, 0x3000, v195
	ds_read2_b64 v[80:83], v239 offset1:2
	ds_read_b128 v[226:229], v168 offset:6144
	ds_read_b128 v[242:245], v213 offset:32
	ds_read_b128 v[230:233], v168 offset:6208
	ds_read_b128 v[246:249], v213 offset:96
	ds_read_b128 v[234:237], v168 offset:6272
	v_cvt_pk_bf16_f32 v84, v214, v215
	v_cvt_pk_bf16_f32 v85, v216, v217
	v_cvt_pk_bf16_f32 v86, v218, v219
	v_cvt_pk_bf16_f32 v87, v222, v188
	v_cvt_pk_bf16_f32 v88, v96, v97
	v_cvt_pk_bf16_f32 v89, v98, v99
	v_cvt_pk_bf16_f32 v90, v100, v101
	v_cvt_pk_bf16_f32 v91, v102, v189
	v_add_u32_e32 v240, 0x4000, v195
	s_waitcnt lgkmcnt(5)
	v_mfma_f32_32x32x16_bf16 v[48:63], v[80:83], v[84:87], v[48:63]
	v_mfma_f32_32x32x16_bf16 v[32:47], v[80:83], v[88:91], v[32:47]
	ds_read2_b64 v[80:83], v240 offset0:32 offset1:34
	ds_read2_b64 v[214:217], v239 offset0:4 offset1:6
	ds_read2_b64 v[222:225], v240 offset0:36 offset1:38
	s_waitcnt lgkmcnt(2)
	v_mfma_f32_32x32x16_bf16 v[16:31], v[80:83], v[84:87], v[16:31]
	v_add_f32_e32 v84, 0, v96
	v_add_f32_e32 v84, v97, v84
	v_add_f32_e32 v84, v98, v84
	v_add_f32_e32 v84, v99, v84
	v_add_f32_e32 v84, v100, v84
	v_add_f32_e32 v84, v101, v84
	v_add_f32_e32 v195, v102, v84
	v_mfma_f32_32x32x16_bf16 v[0:15], v[80:83], v[88:91], v[0:15]
	v_mfma_f32_32x32x16_bf16 v[80:95], v[226:229], v[152:155], v[64:79]
	v_mfma_f32_32x32x16_bf16 v[96:111], v[226:229], v[156:159], v[64:79]
	ds_read_b128 v[226:229], v213 offset:160
	v_mfma_f32_32x32x16_bf16 v[80:95], v[242:245], v[136:139], v[80:95]
	v_mfma_f32_32x32x16_bf16 v[96:111], v[242:245], v[140:143], v[96:111]
	v_mfma_f32_32x32x16_bf16 v[80:95], v[230:233], v[144:147], v[80:95]
	v_mfma_f32_32x32x16_bf16 v[96:111], v[230:233], v[148:151], v[96:111]
	v_mfma_f32_32x32x16_bf16 v[80:95], v[246:249], v[112:115], v[80:95]
	v_mfma_f32_32x32x16_bf16 v[96:111], v[246:249], v[124:127], v[96:111]
	v_mfma_f32_32x32x16_bf16 v[80:95], v[234:237], v[128:131], v[80:95]
	v_mfma_f32_32x32x16_bf16 v[96:111], v[234:237], v[132:135], v[96:111]
	s_waitcnt lgkmcnt(0)
; #define MFMA(a, b, c) __builtin_amdgcn_mfma_f32_32x32x16_bf16((a), (b), (c), 0, 0, 0)
; DI unsigned pk_bf16(float lo, float hi) { f32x2v v = {lo, hi}; bf16x2v b = __builtin_convertvector(v, bf16x2v); return __builtin_bit_cast(unsigned, b); }
; #define SB_ __builtin_amdgcn_sched_barrier(0)
; #define ATT64_STORE(base) do { \
;     { uint2* d = (uint2*)((base) + vlo0); d[0] = make_uint2(rv0.x, rv0.y); d[1] = make_uint2(rv0.z, rv0.w); } } while (0)
; DI void attn_item64(const Params& p, int it, char* smem) {
;     ...
;       { const bf16x8 kf = *(const bf16x8*)(kpe); sa = MFMA(kf, qfa[0], sinit); sb = MFMA(kf, qfb[0], sinit); }
; #pragma unroll
;       for (int c = 1; c < 6; ++c) { const bf16x8 kf = *(const bf16x8*)(((c & 1) ? kpo : kpe) + c * 32); sa = MFMA(kf, qfa[c], sa); sb = MFMA(kf, qfb[c], sb); }
;       SB_;
;       float lsa = 0.f, lsb = 0.f;
; #pragma unroll
;       for (int i = 0; i < 16; ++i) { const float e = __builtin_amdgcn_exp2f(sa[i]); sa[i] = e; lsa += e; const float f = __builtin_amdgcn_exp2f(sb[i]); sb[i] = f; lsb += f; }
;       la += lsa; lb += lsb;
;       SB_;
; #pragma unroll
;       for (int s2 = 0; s2 < 2; ++s2) {
;         uint4 pu, pv;
;         pu.x = pk_bf16(sa[8 * s2 + 0], sa[8 * s2 + 1]); pu.y = pk_bf16(sa[8 * s2 + 2], sa[8 * s2 + 3]); pu.z = pk_bf16(sa[8 * s2 + 4], sa[8 * s2 + 5]); pu.w = pk_bf16(sa[8 * s2 + 6], sa[8 * s2 + 7]);
;         pv.x = pk_bf16(sb[8 * s2 + 0], sb[8 * s2 + 1]); pv.y = pk_bf16(sb[8 * s2 + 2], sb[8 * s2 + 3]); pv.z = pk_bf16(sb[8 * s2 + 4], sb[8 * s2 + 5]); pv.w = pk_bf16(sb[8 * s2 + 6], sb[8 * s2 + 7]);
;         const bf16x8 pa_ = __builtin_bit_cast(bf16x8, pu), pb_ = __builtin_bit_cast(bf16x8, pv);
; #pragma unroll
;         for (int vt = 0; vt < 2; ++vt) {
;           const char* vp = cur + KBYTES + (vt * 32 + r) * VROW + (t2 * 32 + 16 * s2 + 4 * hh) * 2;
;           const uint2 lo = *(const uint2*)(vp), hi = *(const uint2*)(vp + 16);
;           uint4 vu; vu.x = lo.x; vu.y = lo.y; vu.z = hi.x; vu.w = hi.y;
;           const bf16x8 vf = __builtin_bit_cast(bf16x8, vu);
;           oa[vt] = MFMA(vf, pa_, oa[vt]);
;           ob[vt] = MFMA(vf, pb_, ob[vt]);
;         }
;       }
;       SB_;
;     }
;     SB_;
;     if (more) { char* nxt = smem + ((kt + 1) & 1) * STAGE; ATT64_STORE(nxt); }
;     __syncthreads();
	v_mfma_f32_32x32x16_bf16 v[80:95], v[226:229], v[116:119], v[80:95]
	v_mfma_f32_32x32x16_bf16 v[96:111], v[226:229], v[120:123], v[96:111]
	s_waitcnt vmcnt(0)
	ds_write2_b64 v238, v[160:161], v[162:163] offset1:1
	s_nop 10
	v_exp_f32_e32 v168, v80
	v_exp_f32_e32 v213, v81
	v_exp_f32_e32 v233, v96
	v_exp_f32_e32 v96, v82
	v_exp_f32_e32 v234, v97
	v_exp_f32_e32 v97, v83
	v_add_f32_e32 v80, 0, v168
	v_exp_f32_e32 v235, v98
	v_exp_f32_e32 v98, v84
	v_add_f32_e32 v80, v213, v80
	v_exp_f32_e32 v236, v99
	v_exp_f32_e32 v99, v85
	v_add_f32_e32 v80, v96, v80
	v_add_f32_e32 v80, v97, v80
	v_add_f32_e32 v80, v98, v80
	v_exp_f32_e32 v237, v100
	v_exp_f32_e32 v241, v101
	v_exp_f32_e32 v100, v86
	v_exp_f32_e32 v101, v102
	v_exp_f32_e32 v102, v87
	v_exp_f32_e32 v103, v103
	v_exp_f32_e32 v218, v88
	v_exp_f32_e32 v219, v104
	v_exp_f32_e32 v104, v89
	v_exp_f32_e32 v105, v105
	v_exp_f32_e32 v226, v90
	v_exp_f32_e32 v227, v106
	v_exp_f32_e32 v106, v91
	v_exp_f32_e32 v107, v107
	v_exp_f32_e32 v228, v92
	v_exp_f32_e32 v229, v108
	v_exp_f32_e32 v108, v93
	v_exp_f32_e32 v109, v109
	v_exp_f32_e32 v230, v94
	v_exp_f32_e32 v231, v110
	v_exp_f32_e32 v110, v95
	v_exp_f32_e32 v111, v111
	v_add_f32_e32 v232, v99, v80
	v_cvt_pk_bf16_f32 v80, v186, v190
	v_cvt_pk_bf16_f32 v81, v192, v180
	v_cvt_pk_bf16_f32 v82, v182, v184
	v_cvt_pk_bf16_f32 v83, v176, v178
	v_cvt_pk_bf16_f32 v84, v187, v191
	v_cvt_pk_bf16_f32 v85, v193, v181
	v_mfma_f32_32x32x16_bf16 v[48:63], v[214:217], v[80:83], v[48:63]
	v_cvt_pk_bf16_f32 v86, v183, v185
	v_cvt_pk_bf16_f32 v87, v177, v179
	v_cvt_pk_bf16_f32 v88, v233, v234
	v_cvt_pk_bf16_f32 v89, v235, v236
	v_cvt_pk_bf16_f32 v90, v237, v241
	v_cvt_pk_bf16_f32 v91, v101, v103
	v_mfma_f32_32x32x16_bf16 v[16:31], v[222:225], v[80:83], v[16:31]
	ds_read2_b64 v[80:83], v239 offset0:8 offset1:10
	v_mfma_f32_32x32x16_bf16 v[32:47], v[214:217], v[84:87], v[32:47]
	v_mfma_f32_32x32x16_bf16 v[0:15], v[222:225], v[84:87], v[0:15]
	v_cvt_pk_bf16_f32 v84, v168, v213
	v_cvt_pk_bf16_f32 v85, v96, v97
	v_cvt_pk_bf16_f32 v86, v98, v99
	v_cvt_pk_bf16_f32 v87, v100, v102
	s_waitcnt lgkmcnt(0)
	s_nop 0
	v_mfma_f32_32x32x16_bf16 v[48:63], v[80:83], v[84:87], v[48:63]
	v_mfma_f32_32x32x16_bf16 v[32:47], v[80:83], v[88:91], v[32:47]
	ds_read2_b64 v[80:83], v240 offset0:40 offset1:42
	ds_read2_b64 v[92:95], v239 offset0:12 offset1:14
	ds_read2_b64 v[96:99], v240 offset0:44 offset1:46
	s_waitcnt lgkmcnt(2)
	v_mfma_f32_32x32x16_bf16 v[16:31], v[80:83], v[84:87], v[16:31]
	v_add_f32_e32 v84, 0, v233
	v_add_f32_e32 v84, v234, v84
	v_add_f32_e32 v84, v235, v84
	v_add_f32_e32 v84, v236, v84
	v_add_f32_e32 v84, v237, v84
	v_add_f32_e32 v233, v241, v84
	v_pk_add_f32 v[84:85], v[188:189], v[194:195]
	v_mfma_f32_32x32x16_bf16 v[0:15], v[80:83], v[88:91], v[0:15]
	v_add_f32_e64 v80, v186, v84
	v_add_f32_e64 v81, v187, v85
	v_add_f32_e64 v90, v100, v232
	v_add_f32_e64 v91, v101, v233
	v_add_f32_e64 v80, v190, v80
	v_add_f32_e64 v81, v191, v81
	v_pk_add_f32 v[90:91], v[102:103], v[90:91]
	v_pk_add_f32 v[84:85], v[192:193], v[80:81]
	v_cvt_pk_bf16_f32 v80, v218, v104
	v_pk_add_f32 v[84:85], v[180:181], v[84:85]
	v_cvt_pk_bf16_f32 v81, v226, v106
	v_pk_add_f32 v[84:85], v[182:183], v[84:85]
	v_cvt_pk_bf16_f32 v82, v228, v108
	v_cvt_pk_bf16_f32 v83, v230, v110
	v_pk_add_f32 v[88:89], v[184:185], v[84:85]
	v_cvt_pk_bf16_f32 v84, v219, v105
	v_cvt_pk_bf16_f32 v85, v227, v107
	v_cvt_pk_bf16_f32 v86, v229, v109
	v_cvt_pk_bf16_f32 v87, v231, v111
	v_pk_add_f32 v[90:91], v[218:219], v[90:91]
	s_waitcnt lgkmcnt(1)
	v_mfma_f32_32x32x16_bf16 v[48:63], v[92:95], v[80:83], v[48:63]
	v_add_f32_e64 v90, v104, v90
	v_add_f32_e64 v91, v105, v91
	v_add_f32_e64 v88, v176, v88
	v_add_f32_e64 v89, v177, v89
	v_add_f32_e64 v88, v178, v88
	v_add_f32_e64 v89, v179, v89
	v_pk_add_f32 v[88:89], v[166:167], v[88:89]
	v_mfma_f32_32x32x16_bf16 v[32:47], v[92:95], v[84:87], v[32:47]
	s_waitcnt lgkmcnt(0)
	v_mfma_f32_32x32x16_bf16 v[16:31], v[96:99], v[80:83], v[16:31]
	v_add_f32_e64 v80, v226, v90
	v_add_f32_e64 v81, v227, v91
	v_add_f32_e64 v80, v106, v80
	v_add_f32_e64 v81, v107, v81
	v_add_f32_e64 v80, v228, v80
	v_add_f32_e64 v81, v229, v81
	v_pk_add_f32 v[80:81], v[108:109], v[80:81]
	v_mfma_f32_32x32x16_bf16 v[0:15], v[96:99], v[84:87], v[0:15]
	v_add_f32_e64 v80, v230, v80
	v_add_f32_e64 v81, v231, v81
	v_add_f32_e64 v80, v110, v80
	v_add_f32_e64 v81, v111, v81
	v_add_f32_e64 v166, v88, v80
	v_add_f32_e64 v167, v89, v81
	s_add_i32 s8, s8, 1
	v_lshl_add_u64 v[170:171], v[170:171], 0, s[30:31]
	v_lshl_add_u64 v[172:173], v[172:173], 0, s[34:35]
	s_cmp_lg_u32 s8, 36
	v_lshl_add_u64 v[174:175], v[174:175], 0, s[34:35]
	s_waitcnt lgkmcnt(0)
	s_barrier
	s_cbranch_scc0 .LBB0_551
